# v109 + W_down conversion loop in P8 unrolled x2 with two alternating load sets (loads two items ahead, copies behind one vmcnt(36))
# baseline (speedup 1.0000x reference)
; __device__ __forceinline__ void transpose_items_pipe(const float* W, int K, int ldw, int src0, int ncols, int blk, int mul, int add, bf16* WT, LAS float* scr, int gw, int NGW, int lane) {
;     ...
;         const int kb = it / nblk, nb = it - kb * nblk, k0 = 64 * kb, nl = 32 * nb;
;         const int drow = (nl / blk) * mul + (nl % blk) + add;
;         const int nit = it + NGW; const bool more = nit < nitems;
;         float nv[32];
;         { const int ld = more ? nit : it;
;           const int kb2 = ld / nblk, nb2 = ld - kb2 * nblk; const float* src = W + (size_t)(64 * kb2) * ldw + src0 + 32 * nb2 + (lane & 31);
; #pragma unroll
;           for (int i = 0; i < 32; ++i) nv[i] = src[(size_t)(2 * i + (lane >> 5)) * ldw]; }
.LBB0_1091:
	s_add_i32 s9, s6, 0xfffffc00
	s_ashr_i32 s0, s9, 31
	s_lshr_b32 s0, s0, 25
	s_add_i32 s0, s9, s0
	s_ashr_i32 s12, s0, 7
	s_lshl_b32 s0, s12, 12
	s_sub_i32 s13, s7, s0
	s_cmpk_lt_i32 s9, 0x5200
	s_cselect_b64 s[0:1], -1, 0
	s_and_b64 vcc, s[0:1], exec
	s_cselect_b32 s9, s6, s9
	s_ashr_i32 s0, s9, 31
	s_lshr_b32 s0, s0, 25
	s_add_i32 s0, s9, s0
	s_ashr_i32 s10, s0, 7
	s_lshl_b32 s0, s10, 6
	s_ashr_i32 s1, s0, 31
	s_lshl_b64 s[0:1], s[0:1], 14
	s_add_u32 s11, s60, s0
	s_addc_u32 s14, s61, s1
	s_lshl_b32 s0, s10, 12
	s_lshl_b32 s1, s9, 5
	s_sub_i32 s0, s1, s0
	s_ashr_i32 s1, s0, 31
	s_lshl_b64 s[0:1], s[0:1], 2
	s_add_u32 s10, s11, s0
	s_addc_u32 s11, s14, s1
	v_mov_b32_e32 v7, v3
	v_lshl_add_u64 v[108:109], s[10:11], 0, v[2:3]
	v_mov_b32_e32 v9, v3
	v_mov_b32_e32 v11, v3
	v_mov_b32_e32 v13, v3
	v_mov_b32_e32 v15, v3
	v_mov_b32_e32 v17, v3
	v_mov_b32_e32 v19, v3
	v_mov_b32_e32 v21, v3
	v_mov_b32_e32 v23, v3
	v_mov_b32_e32 v25, v3
	v_mov_b32_e32 v27, v3
	v_mov_b32_e32 v29, v3
	v_mov_b32_e32 v31, v3
	v_mov_b32_e32 v33, v3
	v_mov_b32_e32 v35, v3
	v_mov_b32_e32 v37, v3
	v_mov_b32_e32 v39, v3
	v_mov_b32_e32 v41, v3
	v_mov_b32_e32 v43, v3
	v_mov_b32_e32 v45, v3
	v_mov_b32_e32 v47, v3
	v_mov_b32_e32 v49, v3
	v_mov_b32_e32 v51, v3
	v_mov_b32_e32 v53, v3
	v_mov_b32_e32 v55, v3
	v_mov_b32_e32 v57, v3
	v_mov_b32_e32 v59, v3
	v_mov_b32_e32 v61, v3
	v_mov_b32_e32 v63, v3
	v_mov_b32_e32 v65, v3
	v_mov_b32_e32 v67, v3
	v_mov_b32_e32 v69, v3
	v_lshl_add_u64 v[110:111], v[108:109], 0, v[6:7]
	v_lshl_add_u64 v[112:113], v[108:109], 0, v[8:9]
	v_lshl_add_u64 v[114:115], v[108:109], 0, v[10:11]
	v_lshl_add_u64 v[116:117], v[108:109], 0, v[12:13]
	v_lshl_add_u64 v[118:119], v[108:109], 0, v[14:15]
	v_lshl_add_u64 v[120:121], v[108:109], 0, v[16:17]
	v_lshl_add_u64 v[122:123], v[108:109], 0, v[18:19]
	v_lshl_add_u64 v[124:125], v[108:109], 0, v[20:21]
	v_lshl_add_u64 v[126:127], v[108:109], 0, v[22:23]
	v_lshl_add_u64 v[128:129], v[108:109], 0, v[24:25]
	v_lshl_add_u64 v[130:131], v[108:109], 0, v[26:27]
	v_lshl_add_u64 v[132:133], v[108:109], 0, v[28:29]
	v_lshl_add_u64 v[134:135], v[108:109], 0, v[30:31]
	v_lshl_add_u64 v[136:137], v[108:109], 0, v[32:33]
	v_lshl_add_u64 v[138:139], v[108:109], 0, v[34:35]
	v_lshl_add_u64 v[140:141], v[108:109], 0, v[36:37]
	v_lshl_add_u64 v[142:143], v[108:109], 0, v[38:39]
	v_lshl_add_u64 v[144:145], v[108:109], 0, v[40:41]
	s_waitcnt vmcnt(0)
	v_lshl_add_u64 v[146:147], v[108:109], 0, v[42:43]
	v_lshl_add_u64 v[148:149], v[108:109], 0, v[44:45]
	v_lshl_add_u64 v[150:151], v[108:109], 0, v[46:47]
	v_lshl_add_u64 v[152:153], v[108:109], 0, v[48:49]
	v_lshl_add_u64 v[154:155], v[108:109], 0, v[50:51]
	v_lshl_add_u64 v[156:157], v[108:109], 0, v[52:53]
	v_lshl_add_u64 v[158:159], v[108:109], 0, v[54:55]
	v_lshl_add_u64 v[160:161], v[108:109], 0, v[56:57]
	v_lshl_add_u64 v[162:163], v[108:109], 0, v[58:59]
	v_lshl_add_u64 v[164:165], v[108:109], 0, v[60:61]
	v_lshl_add_u64 v[166:167], v[108:109], 0, v[62:63]
	v_lshl_add_u64 v[168:169], v[108:109], 0, v[64:65]
	v_lshl_add_u64 v[170:171], v[108:109], 0, v[66:67]
	v_lshl_add_u64 v[108:109], v[108:109], 0, v[68:69]
	global_load_dword v7, v[110:111], off
	global_load_dword v9, v[112:113], off
	global_load_dword v11, v[114:115], off
	global_load_dword v13, v[116:117], off
	global_load_dword v15, v[118:119], off
	global_load_dword v17, v[120:121], off
	global_load_dword v19, v[122:123], off
	global_load_dword v21, v[124:125], off
	global_load_dword v23, v[126:127], off
	global_load_dword v25, v[128:129], off
	global_load_dword v27, v[130:131], off
	global_load_dword v29, v[132:133], off
	global_load_dword v31, v[134:135], off
	global_load_dword v33, v[136:137], off
	global_load_dword v35, v[138:139], off
	global_load_dword v37, v[140:141], off
	global_load_dword v39, v[158:159], off
	global_load_dword v41, v[160:161], off
	global_load_dword v43, v[162:163], off
	global_load_dword v45, v[164:165], off
	global_load_dword v47, v[166:167], off
	global_load_dword v49, v[168:169], off
	global_load_dword v51, v[170:171], off
	global_load_dword v53, v[108:109], off
	global_load_dword v55, v[142:143], off
	global_load_dword v57, v[144:145], off
	global_load_dword v59, v[146:147], off
	global_load_dword v61, v[148:149], off
	global_load_dword v63, v[150:151], off
	global_load_dword v65, v[152:153], off
	global_load_dword v67, v[154:155], off
	global_load_dword v69, v[156:157], off
	s_add_i32 s9, s6, 0xfffffc00
	s_add_i32 s32, s6, 0x400
	s_cmpk_lt_i32 s9, 0x4e00
	s_cselect_b32 s9, s32, s9
	s_ashr_i32 s0, s9, 31
	s_lshr_b32 s0, s0, 25
	s_add_i32 s0, s9, s0
	s_ashr_i32 s10, s0, 7
	s_lshl_b32 s0, s10, 6
	s_ashr_i32 s1, s0, 31
	s_lshl_b64 s[0:1], s[0:1], 14
	s_add_u32 s11, s60, s0
	s_addc_u32 s14, s61, s1
	s_lshl_b32 s0, s10, 12
	s_lshl_b32 s1, s9, 5
	s_sub_i32 s0, s1, s0
	s_ashr_i32 s1, s0, 31
	s_lshl_b64 s[0:1], s[0:1], 2
	s_add_u32 s10, s11, s0
	s_addc_u32 s11, s14, s1
	v_lshl_add_u64 v[108:109], s[10:11], 0, v[2:3]
	v_mad_u64_u32 v[110:111], s[18:19], v6, 1, v[108:109]
	v_mad_u64_u32 v[112:113], s[18:19], v8, 1, v[108:109]
	v_mad_u64_u32 v[114:115], s[18:19], v10, 1, v[108:109]
	v_mad_u64_u32 v[116:117], s[18:19], v12, 1, v[108:109]
	v_mad_u64_u32 v[118:119], s[18:19], v14, 1, v[108:109]
	v_mad_u64_u32 v[120:121], s[18:19], v16, 1, v[108:109]
	v_mad_u64_u32 v[122:123], s[18:19], v18, 1, v[108:109]
	v_mad_u64_u32 v[124:125], s[18:19], v20, 1, v[108:109]
	v_mad_u64_u32 v[126:127], s[18:19], v22, 1, v[108:109]
	v_mad_u64_u32 v[128:129], s[18:19], v24, 1, v[108:109]
	v_mad_u64_u32 v[130:131], s[18:19], v26, 1, v[108:109]
	v_mad_u64_u32 v[132:133], s[18:19], v28, 1, v[108:109]
; #define LAS __attribute__((address_space(3)))
; #define LDS_WAIT() asm volatile("s_waitcnt lgkmcnt(0)" ::: "memory")
; __device__ __forceinline__ unsigned pk2(float lo, float hi) { const f32x2c v = {lo, hi}; return __builtin_bit_cast(unsigned, __builtin_convertvector(v, bf16x2c)); }
; __device__ __forceinline__ void transpose_items_pipe(const float* W, int K, int ldw, int src0, int ncols, int blk, int mul, int add, bf16* WT, LAS float* scr, int gw, int NGW, int lane) {
;     ...
;         { const int ld = more ? nit : it;
;           const int kb2 = ld / nblk, nb2 = ld - kb2 * nblk; const float* src = W + (size_t)(64 * kb2) * ldw + src0 + 32 * nb2 + (lane & 31);
; #pragma unroll
;           for (int i = 0; i < 32; ++i) nv[i] = src[(size_t)(2 * i + (lane >> 5)) * ldw]; }
;         asm volatile("" ::: "memory");
; #pragma unroll
;         for (int i = 0; i < 32; ++i) scr[(2 * i + (lane >> 5)) * 33 + (lane & 31)] = tv[i];
;         LDS_WAIT(); asm volatile("" ::: "memory");
;         const int c = lane & 7;
; #pragma unroll
;         for (int j = 0; j < 4; ++j) { const int n = (lane >> 3) + 8 * j; const LAS float* s = scr + (8 * c) * 33 + n;
;             v4u o; o.x = pk2(s[0 * 33], s[1 * 33]); o.y = pk2(s[2 * 33], s[3 * 33]); o.z = pk2(s[4 * 33], s[5 * 33]); o.w = pk2(s[6 * 33], s[7 * 33]);
;             *(v4u*)(WT + (size_t)(drow + n) * K + k0 + 8 * c) = o; }
	v_mad_u64_u32 v[134:135], s[18:19], v30, 1, v[108:109]
	v_mad_u64_u32 v[136:137], s[18:19], v32, 1, v[108:109]
	v_mad_u64_u32 v[138:139], s[18:19], v34, 1, v[108:109]
	v_mad_u64_u32 v[140:141], s[18:19], v36, 1, v[108:109]
	v_mad_u64_u32 v[142:143], s[18:19], v38, 1, v[108:109]
	v_mad_u64_u32 v[144:145], s[18:19], v40, 1, v[108:109]
	v_mad_u64_u32 v[146:147], s[18:19], v42, 1, v[108:109]
	v_mad_u64_u32 v[148:149], s[18:19], v44, 1, v[108:109]
	v_mad_u64_u32 v[150:151], s[18:19], v46, 1, v[108:109]
	v_mad_u64_u32 v[152:153], s[18:19], v48, 1, v[108:109]
	v_mad_u64_u32 v[154:155], s[18:19], v50, 1, v[108:109]
	v_mad_u64_u32 v[156:157], s[18:19], v52, 1, v[108:109]
	v_mad_u64_u32 v[158:159], s[18:19], v54, 1, v[108:109]
	v_mad_u64_u32 v[160:161], s[18:19], v56, 1, v[108:109]
	v_mad_u64_u32 v[162:163], s[18:19], v58, 1, v[108:109]
	v_mad_u64_u32 v[164:165], s[18:19], v60, 1, v[108:109]
	v_mad_u64_u32 v[166:167], s[18:19], v62, 1, v[108:109]
	v_mad_u64_u32 v[168:169], s[18:19], v64, 1, v[108:109]
	v_mad_u64_u32 v[170:171], s[18:19], v66, 1, v[108:109]
	v_mad_u64_u32 v[108:109], s[18:19], v68, 1, v[108:109]
	global_load_dword v220, v[110:111], off
	global_load_dword v221, v[112:113], off
	global_load_dword v222, v[114:115], off
	global_load_dword v223, v[116:117], off
	global_load_dword v224, v[118:119], off
	global_load_dword v225, v[120:121], off
	global_load_dword v226, v[122:123], off
	global_load_dword v227, v[124:125], off
	global_load_dword v228, v[126:127], off
	global_load_dword v229, v[128:129], off
	global_load_dword v230, v[130:131], off
	global_load_dword v231, v[132:133], off
	global_load_dword v232, v[134:135], off
	global_load_dword v233, v[136:137], off
	global_load_dword v234, v[138:139], off
	global_load_dword v235, v[140:141], off
	global_load_dword v236, v[158:159], off
	global_load_dword v237, v[160:161], off
	global_load_dword v238, v[162:163], off
	global_load_dword v239, v[164:165], off
	global_load_dword v240, v[166:167], off
	global_load_dword v241, v[168:169], off
	global_load_dword v242, v[170:171], off
	global_load_dword v243, v[108:109], off
	global_load_dword v244, v[142:143], off
	global_load_dword v245, v[144:145], off
	global_load_dword v246, v[146:147], off
	global_load_dword v247, v[148:149], off
	global_load_dword v248, v[150:151], off
	global_load_dword v249, v[152:153], off
	global_load_dword v250, v[154:155], off
	global_load_dword v251, v[156:157], off
	v_add_u32_e32 v107, 0x400, v106
	v_add_u32_e32 v174, 0x800, v106
	v_add_u32_e32 v175, 0xc00, v106
	v_add_u32_e32 v176, 0x1000, v106
	v_add_u32_e32 v177, 0x1400, v106
	v_add_u32_e32 v178, 0x1800, v106
	v_add_u32_e32 v179, 0x1c00, v106
	ds_write2_b32 v106, v76, v75 offset1:66
	ds_write2_b32 v106, v74, v73 offset0:132 offset1:198
	ds_write2_b32 v107, v72, v71 offset0:8 offset1:74
	ds_write2_b32 v107, v70, v1 offset0:140 offset1:206
	ds_write2_b32 v174, v84, v83 offset0:16 offset1:82
	ds_write2_b32 v174, v82, v81 offset0:148 offset1:214
	ds_write2_b32 v175, v80, v79 offset0:24 offset1:90
	ds_write2_b32 v175, v78, v77 offset0:156 offset1:222
	ds_write2_b32 v176, v92, v91 offset0:32 offset1:98
	ds_write2_b32 v176, v90, v89 offset0:164 offset1:230
	ds_write2_b32 v177, v88, v87 offset0:40 offset1:106
	ds_write2_b32 v177, v86, v85 offset0:172 offset1:238
	ds_write2_b32 v178, v105, v104 offset0:48 offset1:114
	ds_write2_b32 v178, v103, v102 offset0:180 offset1:246
	ds_write2_b32 v179, v101, v100 offset0:56 offset1:122
	ds_write2_b32 v179, v99, v98 offset0:188 offset1:254
	s_waitcnt lgkmcnt(0)
	s_ashr_i32 s1, s13, 31
	s_lshl_b32 s0, s12, 6
	s_lshr_b32 s9, s1, 2
	ds_read2_b32 v[74:75], v94 offset0:33 offset1:41
	ds_read2_b32 v[76:77], v94 offset1:8
	ds_read2_b32 v[78:79], v94 offset0:66 offset1:74
	ds_read2_b32 v[80:81], v94 offset0:99 offset1:107
	ds_read2_b32 v[82:83], v94 offset0:132 offset1:140
	ds_read2_b32 v[84:85], v94 offset0:165 offset1:173
	ds_read2_b32 v[86:87], v94 offset0:198 offset1:206
	ds_read2_b32 v[88:89], v94 offset0:231 offset1:239
	s_ashr_i32 s1, s0, 31
	s_add_i32 s9, s13, s9
	ds_read2_b32 v[100:101], v94 offset0:49 offset1:57
	ds_read2_b32 v[102:103], v94 offset0:16 offset1:24
	ds_read2_b32 v[104:105], v94 offset0:82 offset1:90
	ds_read2_b32 v[108:109], v94 offset0:115 offset1:123
	ds_read2_b32 v[110:111], v94 offset0:148 offset1:156
	ds_read2_b32 v[112:113], v94 offset0:181 offset1:189
	ds_read2_b32 v[114:115], v94 offset0:214 offset1:222
	ds_read2_b32 v[116:117], v94 offset0:247 offset1:255
	v_lshl_add_u64 v[172:173], s[0:1], 1, v[4:5]
	s_and_b32 s0, s9, -2.0
	s_sub_i32 s0, s13, s0
	v_or_b32_e32 v1, s0, v93
	v_or_b32_e32 v70, s0, v95
	v_or_b32_e32 v71, s0, v96
	v_or_b32_e32 v72, s0, v97
	v_mad_i64_i32 v[90:91], s[0:1], v1, s8, v[172:173]
	v_mad_i64_i32 v[98:99], s[0:1], v70, s8, v[172:173]
	v_mad_i64_i32 v[118:119], s[0:1], v71, s8, v[172:173]
	v_mad_i64_i32 v[120:121], s[0:1], v72, s8, v[172:173]
	s_waitcnt lgkmcnt(14)
	v_cvt_pk_bf16_f32 v70, v76, v74
	s_waitcnt lgkmcnt(12)
	v_cvt_pk_bf16_f32 v71, v78, v80
	s_waitcnt lgkmcnt(10)
	v_cvt_pk_bf16_f32 v72, v82, v84
	s_waitcnt lgkmcnt(8)
	v_cvt_pk_bf16_f32 v73, v86, v88
	v_cvt_pk_bf16_f32 v74, v77, v75
	v_cvt_pk_bf16_f32 v75, v79, v81
	v_cvt_pk_bf16_f32 v76, v83, v85
	v_cvt_pk_bf16_f32 v77, v87, v89
	s_waitcnt lgkmcnt(6)
	v_cvt_pk_bf16_f32 v78, v102, v100
	s_waitcnt lgkmcnt(4)
	v_cvt_pk_bf16_f32 v79, v104, v108
	s_waitcnt lgkmcnt(2)
	v_cvt_pk_bf16_f32 v80, v110, v112
	s_waitcnt lgkmcnt(0)
	v_cvt_pk_bf16_f32 v81, v114, v116
	v_cvt_pk_bf16_f32 v82, v103, v101
	v_cvt_pk_bf16_f32 v83, v105, v109
	v_cvt_pk_bf16_f32 v84, v111, v113
	v_cvt_pk_bf16_f32 v85, v115, v117
	global_store_dwordx4 v[90:91], v[70:73], off
	global_store_dwordx4 v[98:99], v[74:77], off
	global_store_dwordx4 v[118:119], v[78:81], off
	global_store_dwordx4 v[120:121], v[82:85], off
	s_waitcnt lgkmcnt(0)
; #define LAS __attribute__((address_space(3)))
; #define LDS_WAIT() asm volatile("s_waitcnt lgkmcnt(0)" ::: "memory")
; __device__ __forceinline__ unsigned pk2(float lo, float hi) { const f32x2c v = {lo, hi}; return __builtin_bit_cast(unsigned, __builtin_convertvector(v, bf16x2c)); }
; __device__ __forceinline__ void transpose_items_pipe(const float* W, int K, int ldw, int src0, int ncols, int blk, int mul, int add, bf16* WT, LAS float* scr, int gw, int NGW, int lane) {
;     ...
;     for (;;) {
;         const int kb = it / nblk, nb = it - kb * nblk, k0 = 64 * kb, nl = 32 * nb;
;         const int drow = (nl / blk) * mul + (nl % blk) + add;
;         const int nit = it + NGW; const bool more = nit < nitems;
;         float nv[32];
;         { const int ld = more ? nit : it;
;           const int kb2 = ld / nblk, nb2 = ld - kb2 * nblk; const float* src = W + (size_t)(64 * kb2) * ldw + src0 + 32 * nb2 + (lane & 31);
; #pragma unroll
;           for (int i = 0; i < 32; ++i) nv[i] = src[(size_t)(2 * i + (lane >> 5)) * ldw]; }
;         asm volatile("" ::: "memory");
; #pragma unroll
;         for (int i = 0; i < 32; ++i) scr[(2 * i + (lane >> 5)) * 33 + (lane & 31)] = tv[i];
;         LDS_WAIT(); asm volatile("" ::: "memory");
;         const int c = lane & 7;
; #pragma unroll
;         for (int j = 0; j < 4; ++j) { const int n = (lane >> 3) + 8 * j; const LAS float* s = scr + (8 * c) * 33 + n;
;             v4u o; o.x = pk2(s[0 * 33], s[1 * 33]); o.y = pk2(s[2 * 33], s[3 * 33]); o.z = pk2(s[4 * 33], s[5 * 33]); o.w = pk2(s[6 * 33], s[7 * 33]);
;             *(v4u*)(WT + (size_t)(drow + n) * K + k0 + 8 * c) = o; }
;         LDS_WAIT(); asm volatile("" ::: "memory");
;         if (!more) break;
; #pragma unroll
;         for (int i = 0; i < 32; ++i) tv[i] = nv[i];
;         it = nit;
	s_addk_i32 s6, 0x400
	s_add_i32 s7, s7, 0x8000
	s_waitcnt vmcnt(55)
	v_mov_b32_e32 v80, v31
	s_waitcnt vmcnt(54)
	v_mov_b32_e32 v79, v33
	s_waitcnt vmcnt(53)
	v_mov_b32_e32 v78, v35
	s_waitcnt vmcnt(52)
	v_mov_b32_e32 v77, v37
	s_waitcnt vmcnt(51)
	v_mov_b32_e32 v105, v39
	s_waitcnt vmcnt(50)
	v_mov_b32_e32 v104, v41
	s_waitcnt vmcnt(49)
	v_mov_b32_e32 v103, v43
	s_waitcnt vmcnt(48)
	v_mov_b32_e32 v102, v45
	s_waitcnt vmcnt(47)
	v_mov_b32_e32 v101, v47
	s_waitcnt vmcnt(46)
	v_mov_b32_e32 v100, v49
	s_waitcnt vmcnt(45)
	v_mov_b32_e32 v99, v51
	s_waitcnt vmcnt(44)
	v_mov_b32_e32 v98, v53
	v_mov_b32_e32 v81, v29
	v_mov_b32_e32 v82, v27
	s_waitcnt vmcnt(43)
	v_mov_b32_e32 v92, v55
	s_waitcnt vmcnt(42)
	v_mov_b32_e32 v91, v57
	s_waitcnt vmcnt(41)
	v_mov_b32_e32 v90, v59
	s_waitcnt vmcnt(40)
	v_mov_b32_e32 v89, v61
	v_mov_b32_e32 v83, v25
	v_mov_b32_e32 v84, v23
	v_mov_b32_e32 v1, v21
	v_mov_b32_e32 v70, v19
	s_waitcnt vmcnt(39)
	v_mov_b32_e32 v88, v63
	s_waitcnt vmcnt(38)
	v_mov_b32_e32 v87, v65
	s_waitcnt vmcnt(37)
	v_mov_b32_e32 v86, v67
	s_waitcnt vmcnt(36)
	v_mov_b32_e32 v85, v69
	v_mov_b32_e32 v71, v17
	v_mov_b32_e32 v72, v15
	v_mov_b32_e32 v73, v13
	v_mov_b32_e32 v74, v11
	v_mov_b32_e32 v75, v9
	v_mov_b32_e32 v76, v7
	s_cbranch_vccnz .Lwd_X
	s_branch .Lwd_exit
.Lwd_X:
	s_add_i32 s9, s6, 0xfffffc00
	s_ashr_i32 s0, s9, 31
	s_lshr_b32 s0, s0, 25
	s_add_i32 s0, s9, s0
	s_ashr_i32 s12, s0, 7
	s_lshl_b32 s0, s12, 12
	s_sub_i32 s13, s7, s0
	s_cmpk_lt_i32 s9, 0x5200
	s_cselect_b64 s[0:1], -1, 0
	s_and_b64 vcc, s[0:1], exec
	s_add_i32 s32, s6, 0x400
	s_cmpk_lt_i32 s9, 0x4e00
	s_cselect_b32 s9, s32, s9
	s_ashr_i32 s0, s9, 31
	s_lshr_b32 s0, s0, 25
	s_add_i32 s0, s9, s0
	s_ashr_i32 s10, s0, 7
	s_lshl_b32 s0, s10, 6
	s_ashr_i32 s1, s0, 31
	s_lshl_b64 s[0:1], s[0:1], 14
	s_add_u32 s11, s60, s0
	s_addc_u32 s14, s61, s1
	s_lshl_b32 s0, s10, 12
	s_lshl_b32 s1, s9, 5
	s_sub_i32 s0, s1, s0
	s_ashr_i32 s1, s0, 31
	s_lshl_b64 s[0:1], s[0:1], 2
	s_add_u32 s10, s11, s0
	s_addc_u32 s11, s14, s1
	v_mov_b32_e32 v7, v3
	v_lshl_add_u64 v[108:109], s[10:11], 0, v[2:3]
	v_mov_b32_e32 v9, v3
	v_mov_b32_e32 v11, v3
	v_mov_b32_e32 v13, v3
	v_mov_b32_e32 v15, v3
	v_mov_b32_e32 v17, v3
	v_mov_b32_e32 v19, v3
	v_mov_b32_e32 v21, v3
	v_mov_b32_e32 v23, v3
	v_mov_b32_e32 v25, v3
	v_mov_b32_e32 v27, v3
	v_mov_b32_e32 v29, v3
	v_mov_b32_e32 v31, v3
	v_mov_b32_e32 v33, v3
	v_mov_b32_e32 v35, v3
	v_mov_b32_e32 v37, v3
	v_mov_b32_e32 v39, v3
	v_mov_b32_e32 v41, v3
	v_mov_b32_e32 v43, v3
	v_mov_b32_e32 v45, v3
	v_mov_b32_e32 v47, v3
	v_mov_b32_e32 v49, v3
	v_mov_b32_e32 v51, v3
	v_mov_b32_e32 v53, v3
	v_mov_b32_e32 v55, v3
	v_mov_b32_e32 v57, v3
	v_mov_b32_e32 v59, v3
	v_mov_b32_e32 v61, v3
	v_mov_b32_e32 v63, v3
	v_mov_b32_e32 v65, v3
	v_mov_b32_e32 v67, v3
	v_mov_b32_e32 v69, v3
	v_lshl_add_u64 v[110:111], v[108:109], 0, v[6:7]
	v_lshl_add_u64 v[112:113], v[108:109], 0, v[8:9]
	v_lshl_add_u64 v[114:115], v[108:109], 0, v[10:11]
	v_lshl_add_u64 v[116:117], v[108:109], 0, v[12:13]
	v_lshl_add_u64 v[118:119], v[108:109], 0, v[14:15]
	v_lshl_add_u64 v[120:121], v[108:109], 0, v[16:17]
	v_lshl_add_u64 v[122:123], v[108:109], 0, v[18:19]
	v_lshl_add_u64 v[124:125], v[108:109], 0, v[20:21]
	v_lshl_add_u64 v[126:127], v[108:109], 0, v[22:23]
	v_lshl_add_u64 v[128:129], v[108:109], 0, v[24:25]
	v_lshl_add_u64 v[130:131], v[108:109], 0, v[26:27]
	v_lshl_add_u64 v[132:133], v[108:109], 0, v[28:29]
	v_lshl_add_u64 v[134:135], v[108:109], 0, v[30:31]
	v_lshl_add_u64 v[136:137], v[108:109], 0, v[32:33]
	v_lshl_add_u64 v[138:139], v[108:109], 0, v[34:35]
	v_lshl_add_u64 v[140:141], v[108:109], 0, v[36:37]
	v_lshl_add_u64 v[142:143], v[108:109], 0, v[38:39]
	v_lshl_add_u64 v[144:145], v[108:109], 0, v[40:41]
	v_lshl_add_u64 v[146:147], v[108:109], 0, v[42:43]
	v_lshl_add_u64 v[148:149], v[108:109], 0, v[44:45]
	v_lshl_add_u64 v[150:151], v[108:109], 0, v[46:47]
	v_lshl_add_u64 v[152:153], v[108:109], 0, v[48:49]
	v_lshl_add_u64 v[154:155], v[108:109], 0, v[50:51]
	v_lshl_add_u64 v[156:157], v[108:109], 0, v[52:53]
	v_lshl_add_u64 v[158:159], v[108:109], 0, v[54:55]
	v_lshl_add_u64 v[160:161], v[108:109], 0, v[56:57]
	v_lshl_add_u64 v[162:163], v[108:109], 0, v[58:59]
	v_lshl_add_u64 v[164:165], v[108:109], 0, v[60:61]
	v_lshl_add_u64 v[166:167], v[108:109], 0, v[62:63]
	v_lshl_add_u64 v[168:169], v[108:109], 0, v[64:65]
	v_lshl_add_u64 v[170:171], v[108:109], 0, v[66:67]
	v_lshl_add_u64 v[108:109], v[108:109], 0, v[68:69]
	global_load_dword v7, v[110:111], off
	global_load_dword v9, v[112:113], off
	global_load_dword v11, v[114:115], off
	global_load_dword v13, v[116:117], off
	global_load_dword v15, v[118:119], off
	global_load_dword v17, v[120:121], off
	global_load_dword v19, v[122:123], off
	global_load_dword v21, v[124:125], off
	global_load_dword v23, v[126:127], off
	global_load_dword v25, v[128:129], off
	global_load_dword v27, v[130:131], off
	global_load_dword v29, v[132:133], off
	global_load_dword v31, v[134:135], off
	global_load_dword v33, v[136:137], off
	global_load_dword v35, v[138:139], off
	global_load_dword v37, v[140:141], off
	global_load_dword v39, v[158:159], off
	global_load_dword v41, v[160:161], off
	global_load_dword v43, v[162:163], off
	global_load_dword v45, v[164:165], off
	global_load_dword v47, v[166:167], off
	global_load_dword v49, v[168:169], off
	global_load_dword v51, v[170:171], off
	global_load_dword v53, v[108:109], off
	global_load_dword v55, v[142:143], off
	global_load_dword v57, v[144:145], off
	global_load_dword v59, v[146:147], off
	global_load_dword v61, v[148:149], off
	global_load_dword v63, v[150:151], off
	global_load_dword v65, v[152:153], off
	global_load_dword v67, v[154:155], off
	global_load_dword v69, v[156:157], off
	v_add_u32_e32 v107, 0x400, v106
	v_add_u32_e32 v174, 0x800, v106
	v_add_u32_e32 v175, 0xc00, v106
	v_add_u32_e32 v176, 0x1000, v106
	v_add_u32_e32 v177, 0x1400, v106
	v_add_u32_e32 v178, 0x1800, v106
	v_add_u32_e32 v179, 0x1c00, v106
	ds_write2_b32 v106, v76, v75 offset1:66
	ds_write2_b32 v106, v74, v73 offset0:132 offset1:198
	ds_write2_b32 v107, v72, v71 offset0:8 offset1:74
	ds_write2_b32 v107, v70, v1 offset0:140 offset1:206
	ds_write2_b32 v174, v84, v83 offset0:16 offset1:82
	ds_write2_b32 v174, v82, v81 offset0:148 offset1:214
	ds_write2_b32 v175, v80, v79 offset0:24 offset1:90
	ds_write2_b32 v175, v78, v77 offset0:156 offset1:222
	ds_write2_b32 v176, v92, v91 offset0:32 offset1:98
	ds_write2_b32 v176, v90, v89 offset0:164 offset1:230
	ds_write2_b32 v177, v88, v87 offset0:40 offset1:106
	ds_write2_b32 v177, v86, v85 offset0:172 offset1:238
	ds_write2_b32 v178, v105, v104 offset0:48 offset1:114
	ds_write2_b32 v178, v103, v102 offset0:180 offset1:246
	ds_write2_b32 v179, v101, v100 offset0:56 offset1:122
	ds_write2_b32 v179, v99, v98 offset0:188 offset1:254
	s_waitcnt lgkmcnt(0)
; #define LAS __attribute__((address_space(3)))
; #define LDS_WAIT() asm volatile("s_waitcnt lgkmcnt(0)" ::: "memory")
; __device__ __forceinline__ unsigned pk2(float lo, float hi) { const f32x2c v = {lo, hi}; return __builtin_bit_cast(unsigned, __builtin_convertvector(v, bf16x2c)); }
; __device__ __forceinline__ void transpose_items_pipe(const float* W, int K, int ldw, int src0, int ncols, int blk, int mul, int add, bf16* WT, LAS float* scr, int gw, int NGW, int lane) {
;     ...
;         for (int i = 0; i < 32; ++i) scr[(2 * i + (lane >> 5)) * 33 + (lane & 31)] = tv[i];
;         LDS_WAIT(); asm volatile("" ::: "memory");
;         const int c = lane & 7;
; #pragma unroll
;         for (int j = 0; j < 4; ++j) { const int n = (lane >> 3) + 8 * j; const LAS float* s = scr + (8 * c) * 33 + n;
;             v4u o; o.x = pk2(s[0 * 33], s[1 * 33]); o.y = pk2(s[2 * 33], s[3 * 33]); o.z = pk2(s[4 * 33], s[5 * 33]); o.w = pk2(s[6 * 33], s[7 * 33]);
;             *(v4u*)(WT + (size_t)(drow + n) * K + k0 + 8 * c) = o; }
;         LDS_WAIT(); asm volatile("" ::: "memory");
;         if (!more) break;
; #pragma unroll
;         for (int i = 0; i < 32; ++i) tv[i] = nv[i];
;         it = nit;
	s_ashr_i32 s1, s13, 31
	s_lshl_b32 s0, s12, 6
	s_lshr_b32 s9, s1, 2
	ds_read2_b32 v[74:75], v94 offset0:33 offset1:41
	ds_read2_b32 v[76:77], v94 offset1:8
	ds_read2_b32 v[78:79], v94 offset0:66 offset1:74
	ds_read2_b32 v[80:81], v94 offset0:99 offset1:107
	ds_read2_b32 v[82:83], v94 offset0:132 offset1:140
	ds_read2_b32 v[84:85], v94 offset0:165 offset1:173
	ds_read2_b32 v[86:87], v94 offset0:198 offset1:206
	ds_read2_b32 v[88:89], v94 offset0:231 offset1:239
	s_ashr_i32 s1, s0, 31
	s_add_i32 s9, s13, s9
	ds_read2_b32 v[100:101], v94 offset0:49 offset1:57
	ds_read2_b32 v[102:103], v94 offset0:16 offset1:24
	ds_read2_b32 v[104:105], v94 offset0:82 offset1:90
	ds_read2_b32 v[108:109], v94 offset0:115 offset1:123
	ds_read2_b32 v[110:111], v94 offset0:148 offset1:156
	ds_read2_b32 v[112:113], v94 offset0:181 offset1:189
	ds_read2_b32 v[114:115], v94 offset0:214 offset1:222
	ds_read2_b32 v[116:117], v94 offset0:247 offset1:255
	v_lshl_add_u64 v[172:173], s[0:1], 1, v[4:5]
	s_and_b32 s0, s9, -2.0
	s_sub_i32 s0, s13, s0
	v_or_b32_e32 v1, s0, v93
	v_or_b32_e32 v70, s0, v95
	v_or_b32_e32 v71, s0, v96
	v_or_b32_e32 v72, s0, v97
	v_mad_i64_i32 v[90:91], s[0:1], v1, s8, v[172:173]
	v_mad_i64_i32 v[98:99], s[0:1], v70, s8, v[172:173]
	v_mad_i64_i32 v[118:119], s[0:1], v71, s8, v[172:173]
	v_mad_i64_i32 v[120:121], s[0:1], v72, s8, v[172:173]
	s_waitcnt lgkmcnt(14)
	v_cvt_pk_bf16_f32 v70, v76, v74
	s_waitcnt lgkmcnt(12)
	v_cvt_pk_bf16_f32 v71, v78, v80
	s_waitcnt lgkmcnt(10)
	v_cvt_pk_bf16_f32 v72, v82, v84
	s_waitcnt lgkmcnt(8)
	v_cvt_pk_bf16_f32 v73, v86, v88
	v_cvt_pk_bf16_f32 v74, v77, v75
	v_cvt_pk_bf16_f32 v75, v79, v81
	v_cvt_pk_bf16_f32 v76, v83, v85
	v_cvt_pk_bf16_f32 v77, v87, v89
	s_waitcnt lgkmcnt(6)
	v_cvt_pk_bf16_f32 v78, v102, v100
	s_waitcnt lgkmcnt(4)
	v_cvt_pk_bf16_f32 v79, v104, v108
	s_waitcnt lgkmcnt(2)
	v_cvt_pk_bf16_f32 v80, v110, v112
	s_waitcnt lgkmcnt(0)
	v_cvt_pk_bf16_f32 v81, v114, v116
	v_cvt_pk_bf16_f32 v82, v103, v101
	v_cvt_pk_bf16_f32 v83, v105, v109
	v_cvt_pk_bf16_f32 v84, v111, v113
	v_cvt_pk_bf16_f32 v85, v115, v117
	global_store_dwordx4 v[90:91], v[70:73], off
	global_store_dwordx4 v[98:99], v[74:77], off
	global_store_dwordx4 v[118:119], v[78:81], off
	global_store_dwordx4 v[120:121], v[82:85], off
	s_waitcnt lgkmcnt(0)
	s_addk_i32 s6, 0x400
	s_add_i32 s7, s7, 0x8000
	s_waitcnt vmcnt(36)
	v_mov_b32_e32 v80, v232
	v_mov_b32_e32 v79, v233
	v_mov_b32_e32 v78, v234
	v_mov_b32_e32 v77, v235
	v_mov_b32_e32 v105, v236
	v_mov_b32_e32 v104, v237
	v_mov_b32_e32 v103, v238
	v_mov_b32_e32 v102, v239
	v_mov_b32_e32 v101, v240
	v_mov_b32_e32 v100, v241
	v_mov_b32_e32 v99, v242
	v_mov_b32_e32 v98, v243
	v_mov_b32_e32 v81, v231
	v_mov_b32_e32 v82, v230
	v_mov_b32_e32 v92, v244
	v_mov_b32_e32 v91, v245
	v_mov_b32_e32 v90, v246
	v_mov_b32_e32 v89, v247
	v_mov_b32_e32 v83, v229
	v_mov_b32_e32 v84, v228
	v_mov_b32_e32 v1, v227
	v_mov_b32_e32 v70, v226
	v_mov_b32_e32 v88, v248
	v_mov_b32_e32 v87, v249
	v_mov_b32_e32 v86, v250
	v_mov_b32_e32 v85, v251
	v_mov_b32_e32 v71, v225
	v_mov_b32_e32 v72, v224
	v_mov_b32_e32 v73, v223
	v_mov_b32_e32 v74, v222
	v_mov_b32_e32 v75, v221
	v_mov_b32_e32 v76, v220
	s_cbranch_vccz .Lwd_exit
.Lwd_Y:
	s_add_i32 s9, s6, 0xfffffc00
	s_ashr_i32 s0, s9, 31
	s_lshr_b32 s0, s0, 25
	s_add_i32 s0, s9, s0
	s_ashr_i32 s12, s0, 7
	s_lshl_b32 s0, s12, 12
	s_sub_i32 s13, s7, s0
	s_cmpk_lt_i32 s9, 0x5200
	s_cselect_b64 s[0:1], -1, 0
	s_and_b64 vcc, s[0:1], exec
	s_add_i32 s32, s6, 0x400
	s_cmpk_lt_i32 s9, 0x4e00
	s_cselect_b32 s9, s32, s9
	s_ashr_i32 s0, s9, 31
	s_lshr_b32 s0, s0, 25
	s_add_i32 s0, s9, s0
	s_ashr_i32 s10, s0, 7
	s_lshl_b32 s0, s10, 6
	s_ashr_i32 s1, s0, 31
	s_lshl_b64 s[0:1], s[0:1], 14
	s_add_u32 s11, s60, s0
	s_addc_u32 s14, s61, s1
	s_lshl_b32 s0, s10, 12
	s_lshl_b32 s1, s9, 5
	s_sub_i32 s0, s1, s0
	s_ashr_i32 s1, s0, 31
	s_lshl_b64 s[0:1], s[0:1], 2
	s_add_u32 s10, s11, s0
	s_addc_u32 s11, s14, s1
	v_lshl_add_u64 v[108:109], s[10:11], 0, v[2:3]
	v_mad_u64_u32 v[110:111], s[18:19], v6, 1, v[108:109]
	v_mad_u64_u32 v[112:113], s[18:19], v8, 1, v[108:109]
	v_mad_u64_u32 v[114:115], s[18:19], v10, 1, v[108:109]
	v_mad_u64_u32 v[116:117], s[18:19], v12, 1, v[108:109]
	v_mad_u64_u32 v[118:119], s[18:19], v14, 1, v[108:109]
	v_mad_u64_u32 v[120:121], s[18:19], v16, 1, v[108:109]
	v_mad_u64_u32 v[122:123], s[18:19], v18, 1, v[108:109]
	v_mad_u64_u32 v[124:125], s[18:19], v20, 1, v[108:109]
	v_mad_u64_u32 v[126:127], s[18:19], v22, 1, v[108:109]
	v_mad_u64_u32 v[128:129], s[18:19], v24, 1, v[108:109]
	v_mad_u64_u32 v[130:131], s[18:19], v26, 1, v[108:109]
	v_mad_u64_u32 v[132:133], s[18:19], v28, 1, v[108:109]
	v_mad_u64_u32 v[134:135], s[18:19], v30, 1, v[108:109]
	v_mad_u64_u32 v[136:137], s[18:19], v32, 1, v[108:109]
	v_mad_u64_u32 v[138:139], s[18:19], v34, 1, v[108:109]
	v_mad_u64_u32 v[140:141], s[18:19], v36, 1, v[108:109]
	v_mad_u64_u32 v[142:143], s[18:19], v38, 1, v[108:109]
	v_mad_u64_u32 v[144:145], s[18:19], v40, 1, v[108:109]
	v_mad_u64_u32 v[146:147], s[18:19], v42, 1, v[108:109]
	v_mad_u64_u32 v[148:149], s[18:19], v44, 1, v[108:109]
	v_mad_u64_u32 v[150:151], s[18:19], v46, 1, v[108:109]
	v_mad_u64_u32 v[152:153], s[18:19], v48, 1, v[108:109]
	v_mad_u64_u32 v[154:155], s[18:19], v50, 1, v[108:109]
	v_mad_u64_u32 v[156:157], s[18:19], v52, 1, v[108:109]
	v_mad_u64_u32 v[158:159], s[18:19], v54, 1, v[108:109]
	v_mad_u64_u32 v[160:161], s[18:19], v56, 1, v[108:109]
	v_mad_u64_u32 v[162:163], s[18:19], v58, 1, v[108:109]
	v_mad_u64_u32 v[164:165], s[18:19], v60, 1, v[108:109]
	v_mad_u64_u32 v[166:167], s[18:19], v62, 1, v[108:109]
	v_mad_u64_u32 v[168:169], s[18:19], v64, 1, v[108:109]
; #define LAS __attribute__((address_space(3)))
; #define LDS_WAIT() asm volatile("s_waitcnt lgkmcnt(0)" ::: "memory")
; __device__ __forceinline__ unsigned pk2(float lo, float hi) { const f32x2c v = {lo, hi}; return __builtin_bit_cast(unsigned, __builtin_convertvector(v, bf16x2c)); }
; __device__ __forceinline__ void transpose_items_pipe(const float* W, int K, int ldw, int src0, int ncols, int blk, int mul, int add, bf16* WT, LAS float* scr, int gw, int NGW, int lane) {
;     ...
;         { const int ld = more ? nit : it;
;           const int kb2 = ld / nblk, nb2 = ld - kb2 * nblk; const float* src = W + (size_t)(64 * kb2) * ldw + src0 + 32 * nb2 + (lane & 31);
; #pragma unroll
;           for (int i = 0; i < 32; ++i) nv[i] = src[(size_t)(2 * i + (lane >> 5)) * ldw]; }
;         asm volatile("" ::: "memory");
; #pragma unroll
;         for (int i = 0; i < 32; ++i) scr[(2 * i + (lane >> 5)) * 33 + (lane & 31)] = tv[i];
;         LDS_WAIT(); asm volatile("" ::: "memory");
;         const int c = lane & 7;
; #pragma unroll
;         for (int j = 0; j < 4; ++j) { const int n = (lane >> 3) + 8 * j; const LAS float* s = scr + (8 * c) * 33 + n;
;             v4u o; o.x = pk2(s[0 * 33], s[1 * 33]); o.y = pk2(s[2 * 33], s[3 * 33]); o.z = pk2(s[4 * 33], s[5 * 33]); o.w = pk2(s[6 * 33], s[7 * 33]);
;             *(v4u*)(WT + (size_t)(drow + n) * K + k0 + 8 * c) = o; }
;         LDS_WAIT(); asm volatile("" ::: "memory");
;         if (!more) break;
; #pragma unroll
;         for (int i = 0; i < 32; ++i) tv[i] = nv[i];
;         it = nit;
	v_mad_u64_u32 v[170:171], s[18:19], v66, 1, v[108:109]
	v_mad_u64_u32 v[108:109], s[18:19], v68, 1, v[108:109]
	global_load_dword v220, v[110:111], off
	global_load_dword v221, v[112:113], off
	global_load_dword v222, v[114:115], off
	global_load_dword v223, v[116:117], off
	global_load_dword v224, v[118:119], off
	global_load_dword v225, v[120:121], off
	global_load_dword v226, v[122:123], off
	global_load_dword v227, v[124:125], off
	global_load_dword v228, v[126:127], off
	global_load_dword v229, v[128:129], off
	global_load_dword v230, v[130:131], off
	global_load_dword v231, v[132:133], off
	global_load_dword v232, v[134:135], off
	global_load_dword v233, v[136:137], off
	global_load_dword v234, v[138:139], off
	global_load_dword v235, v[140:141], off
	global_load_dword v236, v[158:159], off
	global_load_dword v237, v[160:161], off
	global_load_dword v238, v[162:163], off
	global_load_dword v239, v[164:165], off
	global_load_dword v240, v[166:167], off
	global_load_dword v241, v[168:169], off
	global_load_dword v242, v[170:171], off
	global_load_dword v243, v[108:109], off
	global_load_dword v244, v[142:143], off
	global_load_dword v245, v[144:145], off
	global_load_dword v246, v[146:147], off
	global_load_dword v247, v[148:149], off
	global_load_dword v248, v[150:151], off
	global_load_dword v249, v[152:153], off
	global_load_dword v250, v[154:155], off
	global_load_dword v251, v[156:157], off
	v_add_u32_e32 v107, 0x400, v106
	v_add_u32_e32 v174, 0x800, v106
	v_add_u32_e32 v175, 0xc00, v106
	v_add_u32_e32 v176, 0x1000, v106
	v_add_u32_e32 v177, 0x1400, v106
	v_add_u32_e32 v178, 0x1800, v106
	v_add_u32_e32 v179, 0x1c00, v106
	ds_write2_b32 v106, v76, v75 offset1:66
	ds_write2_b32 v106, v74, v73 offset0:132 offset1:198
	ds_write2_b32 v107, v72, v71 offset0:8 offset1:74
	ds_write2_b32 v107, v70, v1 offset0:140 offset1:206
	ds_write2_b32 v174, v84, v83 offset0:16 offset1:82
	ds_write2_b32 v174, v82, v81 offset0:148 offset1:214
	ds_write2_b32 v175, v80, v79 offset0:24 offset1:90
	ds_write2_b32 v175, v78, v77 offset0:156 offset1:222
	ds_write2_b32 v176, v92, v91 offset0:32 offset1:98
	ds_write2_b32 v176, v90, v89 offset0:164 offset1:230
	ds_write2_b32 v177, v88, v87 offset0:40 offset1:106
	ds_write2_b32 v177, v86, v85 offset0:172 offset1:238
	ds_write2_b32 v178, v105, v104 offset0:48 offset1:114
	ds_write2_b32 v178, v103, v102 offset0:180 offset1:246
	ds_write2_b32 v179, v101, v100 offset0:56 offset1:122
	ds_write2_b32 v179, v99, v98 offset0:188 offset1:254
	s_waitcnt lgkmcnt(0)
	s_ashr_i32 s1, s13, 31
	s_lshl_b32 s0, s12, 6
	s_lshr_b32 s9, s1, 2
	ds_read2_b32 v[74:75], v94 offset0:33 offset1:41
	ds_read2_b32 v[76:77], v94 offset1:8
	ds_read2_b32 v[78:79], v94 offset0:66 offset1:74
	ds_read2_b32 v[80:81], v94 offset0:99 offset1:107
	ds_read2_b32 v[82:83], v94 offset0:132 offset1:140
	ds_read2_b32 v[84:85], v94 offset0:165 offset1:173
	ds_read2_b32 v[86:87], v94 offset0:198 offset1:206
	ds_read2_b32 v[88:89], v94 offset0:231 offset1:239
	s_ashr_i32 s1, s0, 31
	s_add_i32 s9, s13, s9
	ds_read2_b32 v[100:101], v94 offset0:49 offset1:57
	ds_read2_b32 v[102:103], v94 offset0:16 offset1:24
	ds_read2_b32 v[104:105], v94 offset0:82 offset1:90
	ds_read2_b32 v[108:109], v94 offset0:115 offset1:123
	ds_read2_b32 v[110:111], v94 offset0:148 offset1:156
	ds_read2_b32 v[112:113], v94 offset0:181 offset1:189
	ds_read2_b32 v[114:115], v94 offset0:214 offset1:222
	ds_read2_b32 v[116:117], v94 offset0:247 offset1:255
	v_lshl_add_u64 v[172:173], s[0:1], 1, v[4:5]
	s_and_b32 s0, s9, -2.0
	s_sub_i32 s0, s13, s0
	v_or_b32_e32 v1, s0, v93
	v_or_b32_e32 v70, s0, v95
	v_or_b32_e32 v71, s0, v96
	v_or_b32_e32 v72, s0, v97
	v_mad_i64_i32 v[90:91], s[0:1], v1, s8, v[172:173]
	v_mad_i64_i32 v[98:99], s[0:1], v70, s8, v[172:173]
	v_mad_i64_i32 v[118:119], s[0:1], v71, s8, v[172:173]
	v_mad_i64_i32 v[120:121], s[0:1], v72, s8, v[172:173]
	s_waitcnt lgkmcnt(14)
	v_cvt_pk_bf16_f32 v70, v76, v74
	s_waitcnt lgkmcnt(12)
	v_cvt_pk_bf16_f32 v71, v78, v80
	s_waitcnt lgkmcnt(10)
	v_cvt_pk_bf16_f32 v72, v82, v84
	s_waitcnt lgkmcnt(8)
	v_cvt_pk_bf16_f32 v73, v86, v88
	v_cvt_pk_bf16_f32 v74, v77, v75
	v_cvt_pk_bf16_f32 v75, v79, v81
	v_cvt_pk_bf16_f32 v76, v83, v85
	v_cvt_pk_bf16_f32 v77, v87, v89
	s_waitcnt lgkmcnt(6)
	v_cvt_pk_bf16_f32 v78, v102, v100
	s_waitcnt lgkmcnt(4)
	v_cvt_pk_bf16_f32 v79, v104, v108
	s_waitcnt lgkmcnt(2)
	v_cvt_pk_bf16_f32 v80, v110, v112
	s_waitcnt lgkmcnt(0)
	v_cvt_pk_bf16_f32 v81, v114, v116
	v_cvt_pk_bf16_f32 v82, v103, v101
	v_cvt_pk_bf16_f32 v83, v105, v109
	v_cvt_pk_bf16_f32 v84, v111, v113
	v_cvt_pk_bf16_f32 v85, v115, v117
	global_store_dwordx4 v[90:91], v[70:73], off
	global_store_dwordx4 v[98:99], v[74:77], off
	global_store_dwordx4 v[118:119], v[78:81], off
	global_store_dwordx4 v[120:121], v[82:85], off
	s_waitcnt lgkmcnt(0)
	s_addk_i32 s6, 0x400
	s_add_i32 s7, s7, 0x8000
	s_waitcnt vmcnt(36)
	v_mov_b32_e32 v80, v31
	v_mov_b32_e32 v79, v33
	v_mov_b32_e32 v78, v35
	v_mov_b32_e32 v77, v37
	v_mov_b32_e32 v105, v39
	v_mov_b32_e32 v104, v41
	v_mov_b32_e32 v103, v43
	v_mov_b32_e32 v102, v45
	v_mov_b32_e32 v101, v47
	v_mov_b32_e32 v100, v49
	v_mov_b32_e32 v99, v51
	v_mov_b32_e32 v98, v53
	v_mov_b32_e32 v81, v29
	v_mov_b32_e32 v82, v27
	v_mov_b32_e32 v92, v55
	v_mov_b32_e32 v91, v57
	v_mov_b32_e32 v90, v59
	v_mov_b32_e32 v89, v61
	v_mov_b32_e32 v83, v25
	v_mov_b32_e32 v84, v23
	v_mov_b32_e32 v1, v21
	v_mov_b32_e32 v70, v19
	v_mov_b32_e32 v88, v63
	v_mov_b32_e32 v87, v65
	v_mov_b32_e32 v86, v67
	v_mov_b32_e32 v85, v69
	v_mov_b32_e32 v71, v17
	v_mov_b32_e32 v72, v15
	v_mov_b32_e32 v73, v13
	v_mov_b32_e32 v74, v11
	v_mov_b32_e32 v75, v9
	v_mov_b32_e32 v76, v7
	s_cbranch_vccnz .Lwd_X
; __device__ __forceinline__ unsigned xb_ld(unsigned* p)              { return __hip_atomic_load(p, __ATOMIC_RELAXED, __HIP_MEMORY_SCOPE_AGENT); }
; __device__ __forceinline__ void xcd_barrier_complete(unsigned* bar, unsigned x, unsigned& nloc, unsigned& nx) {
;     const unsigned G = gridDim.x * gridDim.y * gridDim.z;
;     unsigned sum, cnt, mine, sp = 0u;
;     for (;;) {
;         sum = 0u; cnt = 0u; mine = 0u;
; #pragma unroll
;         for (unsigned j = 0; j < 16; ++j) { const unsigned c = xb_ld(&bar[XB_XCNT(j)]); sum += c; cnt += (c > 0u) ? 1u : 0u; mine = (j == x) ? c : mine; }
; __device__ __forceinline__ void xcd_barrier(const XcdBarrier& b) {
;     asm volatile("s_waitcnt vmcnt(0)" ::: "memory");
;     __syncthreads();
;     if (threadIdx.x == 0) {
;         unsigned* bar = b.bar;
;         __builtin_amdgcn_s_waitcnt(0);
;         unsigned nloc = b.st[0], nx = b.st[1];
;         if (nloc == 0u) { xcd_barrier_complete(bar, b.x, nloc, nx); b.st[0] = nloc; b.st[1] = nx; }
.Lwd_exit:
	s_waitcnt vmcnt(0)
.LBB0_1092:
	s_cmp_gt_i32 s67, 9
	s_cselect_b64 s[0:1], -1, 0
	s_and_b64 s[4:5], s[4:5], s[0:1]
	s_andn2_b64 vcc, exec, s[4:5]
	s_cbranch_vccnz .LBB0_1142
	s_waitcnt vmcnt(0)
	v_cmp_eq_u32_e32 vcc, 0, v0
	s_waitcnt vmcnt(0)
	s_barrier
	s_and_saveexec_b64 s[4:5], vcc
	s_cbranch_execz .LBB0_1141
	v_readlane_b32 s6, v254, 6
	s_waitcnt vmcnt(0) expcnt(0) lgkmcnt(0)
	s_nop 0
	v_mov_b32_e32 v1, s6
	ds_read_b32 v3, v1
	ds_read_b32 v1, v1 offset:4
	s_waitcnt lgkmcnt(1)
	v_cmp_ne_u32_e32 vcc, 0, v3
	s_cbranch_vccnz .LBB0_1109
	v_readlane_b32 s6, v254, 1
	v_readlane_b32 s7, v254, 2
	s_load_dwordx2 s[10:11], s[6:7], 0x4
	s_add_u32 s6, s64, 0x4200
	s_addc_u32 s7, s65, 0
	s_add_u32 s8, s64, 0x4400
	s_addc_u32 s9, s65, 0
	s_waitcnt lgkmcnt(0)
	s_mul_i32 s23, s10, s72
	s_add_u32 s10, s64, 0x4500
	s_mul_i32 s23, s23, s11
	s_addc_u32 s11, s65, 0
	s_add_u32 s12, s64, 0x4600
	s_addc_u32 s13, s65, 0
	s_add_u32 s14, s64, 0x4700
	s_addc_u32 s15, s65, 0
	s_add_u32 s16, s64, 0x4800
	s_addc_u32 s17, s65, 0
	s_add_u32 s24, s64, 0x4900
	s_addc_u32 s25, s65, 0
	s_add_u32 s26, s64, 0x4a00
	s_addc_u32 s27, s65, 0
	s_add_u32 s28, s64, 0x4b00
	s_addc_u32 s29, s65, 0
	s_add_u32 s30, s64, 0x4c00
	s_addc_u32 s31, s65, 0
	s_add_u32 s34, s64, 0x4d00
	s_addc_u32 s35, s65, 0
	s_add_u32 s36, s64, 0x4e00
	s_addc_u32 s37, s65, 0
	s_add_u32 s38, s64, 0x4f00
	s_addc_u32 s39, s65, 0
	s_add_u32 s40, s64, 0x5000
	s_addc_u32 s41, s65, 0
	s_add_u32 s42, s64, 0x5100
	s_addc_u32 s43, s65, 0
	s_add_u32 s44, s64, 0x5200
	s_addc_u32 s45, s65, 0
	s_add_u32 s46, s64, 0x5300
	s_addc_u32 s47, s65, 0
	s_mov_b32 s33, 1
	v_mov_b32_e32 v17, 0
	s_branch .LBB0_1097
